# conversion routine: wa/wb/wo handled as one merged item stream (no per-matrix pipeline drain) in P0 and the gate/up L0 slot
# speedup vs baseline: 1.0063x; 1.0063x over previous
;     ...
;     for (int mi = 0; mi < 7 * DEPTH; ++mi) {
;         if (!((mask >> mi) & 1u)) continue;
;         const int l = mi / 7, kind = mi - 7 * l;
;         const float* W; const float* ks = nullptr; bf16_t* WT; int K, N, rm = 0;
;         if (kind == 0)      { W = a.in[2] + (size_t)l * 2048 * 7680;  K = 2048; N = 7680; WT = (bf16_t*)(ws + WS_WIN + l * SZ_WIN); ks = a.in[1] + l * 2048; rm = 3; }
;         else if (kind == 1) { W = a.in[10] + (size_t)l * 1024 * 2048; K = 1024; N = 2048; WT = (bf16_t*)(ws + WS_WA + l * SZ_WA); }
;         else if (kind == 2) { W = a.in[11] + (size_t)l * 1024 * 2048; K = 1024; N = 2048; WT = (bf16_t*)(ws + WS_WB + l * SZ_WB); }
;         else if (kind == 3) { W = a.in[12] + (size_t)l * 2048 * 2048; K = 2048; N = 2048; WT = (bf16_t*)(ws + WS_WO + l * SZ_WO); }
;         else if (kind == 4) { W = a.in[14] + (size_t)l * 2048 * 5632; K = 2048; N = 5632; WT = (bf16_t*)(ws + WS_WGU + l * SZ_WGU); ks = a.in[13] + l * 2048; rm = 1; }
;         else if (kind == 5) { W = a.in[15] + (size_t)l * 2048 * 5632; K = 2048; N = 5632; WT = (bf16_t*)(ws + WS_WGU + l * SZ_WGU); ks = a.in[13] + l * 2048; rm = 2; }
;         else                { W = a.in[16] + (size_t)l * 5632 * 2048; K = 5632; N = 2048; WT = (bf16_t*)(ws + WS_WD + l * SZ_WD); }
;         const int nitems = (K >> 6) * (N >> 5);
;         int ilo = 0, ihi = nitems; if ((fmask >> mi) & 1u) { ilo = (nitems * flo) >> 4; ihi = (nitems * fhi) >> 4; }
;         const int cnt = ihi - ilo;
;         int first = (gw - base) % NGW; if (first < 0) first += NGW;
;         for (int it = first; it < cnt; it += NGW) tr_item(W, K, N, WT, ks, rm, ilo + it, lane);
;         base = (base + cnt) % NGW;
.Lsl_p0_dispatch:
	s_cmp_eq_u32 s46, 0
	s_cbranch_scc1 .Lsl_p0_set0
	s_cmp_eq_u32 s46, 1
	s_cbranch_scc1 .Lsl_p0_set1
	s_branch .LBB0_53
.Lsl_p0_set0:
	v_readlane_b32 s22, v250, 6
	v_readlane_b32 s23, v250, 7
	v_readlane_b32 s24, v250, 36
	v_readlane_b32 s25, v250, 37
	v_readlane_b32 s44, v250, 4
	v_readlane_b32 s45, v250, 5
	v_mul_u32_u24_e32 v104, 0x3c000, v102
	v_lshl_add_u32 v104, v103, 4, v104
	v_mul_u32_u24_e32 v105, 0x4000, v103
	v_lshl_add_u32 v105, v102, 4, v105
	s_mov_b32 s60, 0
	s_add_u32 s24, s24, 0x1c0000
	s_addc_u32 s25, s25, 0
	s_mov_b32 s48, 0x7800
	s_mov_b32 s49, 0x1e0000
	s_movk_i32 s50, 8739
	s_mov_b32 s51, 21
	s_movk_i32 s52, 240
	s_movk_i32 s53, 0x1000
	s_mov_b32 s54, 3
	s_mov_b32 s55, 1
	s_movk_i32 s56, 0
	s_movk_i32 s47, 7680
	s_sub_i32 s4, s12, 0
	s_and_b32 s4, s4, 2047
	s_branch .Lsl_p0_loop
.Lsl_p0_set1:
	v_readlane_b32 s22, v250, 22
	v_readlane_b32 s23, v250, 23
	v_readlane_b32 s24, v250, 36
	v_readlane_b32 s25, v250, 37
	v_mul_u32_u24_e32 v104, 0x10000, v102
	v_lshl_add_u32 v104, v103, 4, v104
	v_mul_u32_u24_e32 v105, 0x2000, v103
	v_lshl_add_u32 v105, v102, 4, v105
	v_mul_u32_u24_e32 v106, 0x4000, v103
	v_lshl_add_u32 v106, v102, 4, v106
	s_mov_b32 s60, 1
	s_add_u32 s24, s24, 0xfffc0000
	s_addc_u32 s25, s25, -1
	s_mov_b32 s48, 0x2000
	s_mov_b32 s49, 0x80000
	s_movk_i32 s50, 1
	s_mov_b32 s51, 6
	s_movk_i32 s52, 64
	s_movk_i32 s53, 0x800
	s_mov_b32 s54, 0
	s_mov_b32 s55, 0
	s_movk_i32 s56, 0
	s_movk_i32 s47, 4096
	s_sub_i32 s4, s12, 1536
	s_and_b32 s4, s4, 2047
	s_branch .Lsl_p0_loop
.Lsl_p0_loop:
	s_cmp_ge_u32 s4, s47
	s_cbranch_scc1 .Lsl_p0_next
	s_add_i32 s16, s4, s56
	s_mov_b32 s57, s53
	v_mov_b32_e32 v44, v105
	s_cmp_eq_u32 s60, 0
	s_cbranch_scc1 .Lsl_p0_nmu1
	s_cmp_ge_u32 s16, 2048
	s_cbranch_scc1 .Lsl_p0_pc5
	s_cmp_ge_u32 s16, 1024
	s_cbranch_scc1 .Lsl_p0_pc4
	v_readlane_b32 s22, v250, 22
	v_readlane_b32 s23, v250, 23
	s_movk_i32 s57, 0x800
	s_mov_b32 s21, 0x3e00000
	v_add_u32_e32 v44, s21, v105
	s_nop 0
	s_branch .Lsl_p0_pj2
.Lsl_p0_pc4:
	v_readlane_b32 s22, v250, 24
	v_readlane_b32 s23, v250, 25
	s_sub_i32 s16, s16, 1024
	s_movk_i32 s57, 0x800
	s_mov_b32 s21, 0x4600000
	v_add_u32_e32 v44, s21, v105
	s_nop 0
	s_branch .Lsl_p0_pj2
.Lsl_p0_pc5:
	v_readlane_b32 s22, v250, 26
	v_readlane_b32 s23, v250, 27
	s_sub_i32 s16, s16, 2048
	s_movk_i32 s57, 0x1000
	s_mov_b32 s21, 0x4e00000
	v_add_u32_e32 v44, s21, v106
	s_nop 0
.Lsl_p0_pj2:
.Lsl_p0_nmu1:
	s_mul_i32 s17, s16, s50
	s_lshr_b32 s17, s17, s51
	s_mul_i32 s19, s17, s52
	s_sub_i32 s18, s16, s19
	s_mul_i32 s19, s17, s49
	s_lshl_b32 s20, s18, 7
	s_add_i32 s19, s19, s20
	v_add_u32_e32 v42, s19, v104
	s_cmp_eq_u32 s55, 0
	s_cbranch_scc1 .Lsl_p0_nks6
	s_lshl_b32 s19, s17, 8
	v_add_u32_e32 v43, s19, v110
	global_load_dwordx4 v[34:37], v43, s[44:45]
	global_load_dwordx4 v[38:41], v43, s[44:45] offset:16

; __device__ __forceinline__ void tr_item(const float* __restrict__ W, int K, int N, bf16_t* WT, const float* __restrict__ kscale, int rowmode, int item, int lane) {
;     const int nblk = N >> 5, kb = item / nblk, nb = item - kb * nblk;
;     const int c = lane >> 3, q = lane & 7, k0 = kb * 64 + c * 8, n0 = nb * 32 + q * 4;
;     f32x4 v[8];
; #pragma unroll
;     for (int i = 0; i < 8; ++i) v[i] = __builtin_nontemporal_load((const f32x4*)(W + (size_t)(k0 + i) * N + n0));
;     if (kscale) { const f32x4 s0 = *(const f32x4*)(kscale + k0), s1 = *(const f32x4*)(kscale + k0 + 4);
; #pragma unroll
;         for (int i = 0; i < 4; ++i) { v[i] = v[i] * s0[i]; v[4 + i] = v[4 + i] * s1[i]; } }
;     int drow;
;     if (rowmode == 0) drow = n0;
;     else if (rowmode == 3) { const int g = n0 - pg8::C_GA; drow = g < 0 ? n0 : pg8::C_GA + (((g & 2047) >> 7) << 8) + ((g >> 11) << 7) + (g & 127); }
;     else drow = ((n0 >> 7) << 8) + (n0 & 127) + (rowmode == 2 ? 128 : 0);
.Lsl_p0_rmd7:
	s_mul_i32 s19, s19, s57
	s_lshl_b32 s20, s17, 7
	s_add_i32 s19, s19, s20
	v_add_u32_e32 v44, s19, v44
	s_add_i32 s4, s4, 2048
	s_cmp_ge_u32 s4, s47
	s_cbranch_scc1 .Lsl_p0_single
	s_add_i32 s16, s4, s56
	s_mov_b32 s58, s53
	v_mov_b32_e32 v45, v105
	s_cmp_eq_u32 s60, 0
	s_cbranch_scc1 .Lsl_p0_nmu9
	s_cmp_ge_u32 s16, 2048
	s_cbranch_scc1 .Lsl_p0_pc13
	s_cmp_ge_u32 s16, 1024
	s_cbranch_scc1 .Lsl_p0_pc12
	v_readlane_b32 s22, v250, 22
	v_readlane_b32 s23, v250, 23
	s_movk_i32 s58, 0x800
	s_mov_b32 s21, 0x3e00000
	v_add_u32_e32 v45, s21, v105
	s_nop 0
	s_branch .Lsl_p0_pj10
.Lsl_p0_pc12:
	v_readlane_b32 s22, v250, 24
	v_readlane_b32 s23, v250, 25
	s_sub_i32 s16, s16, 1024
	s_movk_i32 s58, 0x800
	s_mov_b32 s21, 0x4600000
	v_add_u32_e32 v45, s21, v105
	s_nop 0
	s_branch .Lsl_p0_pj10
.Lsl_p0_pc13:
	v_readlane_b32 s22, v250, 26
	v_readlane_b32 s23, v250, 27
	s_sub_i32 s16, s16, 2048
	s_movk_i32 s58, 0x1000
	s_mov_b32 s21, 0x4e00000
	v_add_u32_e32 v45, s21, v106
	s_nop 0
.Lsl_p0_pj10:
.Lsl_p0_nmu9:
	s_mul_i32 s17, s16, s50
	s_lshr_b32 s17, s17, s51
	s_mul_i32 s19, s17, s52
	s_sub_i32 s18, s16, s19
	s_mul_i32 s19, s17, s49
	s_lshl_b32 s20, s18, 7
	s_add_i32 s19, s19, s20
	v_add_u32_e32 v42, s19, v104
	s_cmp_eq_u32 s55, 0
	s_cbranch_scc1 .Lsl_p0_nks14
	s_lshl_b32 s19, s17, 8
	v_add_u32_e32 v43, s19, v110
	global_load_dwordx4 v[78:81], v43, s[44:45]
	global_load_dwordx4 v[82:85], v43, s[44:45] offset:16

; __device__ __forceinline__ void tr_item(const float* __restrict__ W, int K, int N, bf16_t* WT, const float* __restrict__ kscale, int rowmode, int item, int lane) {
;     const int nblk = N >> 5, kb = item / nblk, nb = item - kb * nblk;
;     const int c = lane >> 3, q = lane & 7, k0 = kb * 64 + c * 8, n0 = nb * 32 + q * 4;
;     f32x4 v[8];
; #pragma unroll
;     for (int i = 0; i < 8; ++i) v[i] = __builtin_nontemporal_load((const f32x4*)(W + (size_t)(k0 + i) * N + n0));
;     if (kscale) { const f32x4 s0 = *(const f32x4*)(kscale + k0), s1 = *(const f32x4*)(kscale + k0 + 4);
; #pragma unroll
;         for (int i = 0; i < 4; ++i) { v[i] = v[i] * s0[i]; v[4 + i] = v[4 + i] * s1[i]; } }
;     int drow;
;     if (rowmode == 0) drow = n0;
;     else if (rowmode == 3) { const int g = n0 - pg8::C_GA; drow = g < 0 ? n0 : pg8::C_GA + (((g & 2047) >> 7) << 8) + ((g >> 11) << 7) + (g & 127); }
;     else drow = ((n0 >> 7) << 8) + (n0 & 127) + (rowmode == 2 ? 128 : 0);
.Lsl_p0_rmd15:
	s_mul_i32 s19, s19, s58
	s_lshl_b32 s20, s17, 7
	s_add_i32 s19, s19, s20
	v_add_u32_e32 v45, s19, v45
	s_add_i32 s4, s4, 2048
	s_cmp_ge_u32 s4, s47
	s_cbranch_scc1 .Lsl_p0_pair
	s_add_i32 s16, s4, s56
	s_mov_b32 s59, s53
	v_mov_b32_e32 v111, v105
	s_cmp_eq_u32 s60, 0
	s_cbranch_scc1 .Lsl_p0_nmu17
	s_cmp_ge_u32 s16, 2048
	s_cbranch_scc1 .Lsl_p0_pc21
	s_cmp_ge_u32 s16, 1024
	s_cbranch_scc1 .Lsl_p0_pc20
	v_readlane_b32 s22, v250, 22
	v_readlane_b32 s23, v250, 23
	s_movk_i32 s59, 0x800
	s_mov_b32 s21, 0x3e00000
	v_add_u32_e32 v111, s21, v105
	s_nop 0
	s_branch .Lsl_p0_pj18
.Lsl_p0_pc20:
	v_readlane_b32 s22, v250, 24
	v_readlane_b32 s23, v250, 25
	s_sub_i32 s16, s16, 1024
	s_movk_i32 s59, 0x800
	s_mov_b32 s21, 0x4600000
	v_add_u32_e32 v111, s21, v105
	s_nop 0
	s_branch .Lsl_p0_pj18
.Lsl_p0_pc21:
	v_readlane_b32 s22, v250, 26
	v_readlane_b32 s23, v250, 27
	s_sub_i32 s16, s16, 2048
	s_movk_i32 s59, 0x1000
	s_mov_b32 s21, 0x4e00000
	v_add_u32_e32 v111, s21, v106
	s_nop 0
.Lsl_p0_pj18:
.Lsl_p0_nmu17:
	s_mul_i32 s17, s16, s50
	s_lshr_b32 s17, s17, s51
	s_mul_i32 s19, s17, s52
	s_sub_i32 s18, s16, s19
	s_mul_i32 s19, s17, s49
	s_lshl_b32 s20, s18, 7
	s_add_i32 s19, s19, s20
	v_add_u32_e32 v42, s19, v104
	s_cmp_eq_u32 s55, 0
	s_cbranch_scc1 .Lsl_p0_nks22
	s_lshl_b32 s19, s17, 8
	v_add_u32_e32 v43, s19, v110
	global_load_dwordx4 v[144:147], v43, s[44:45]
	global_load_dwordx4 v[148:151], v43, s[44:45] offset:16

; __device__ __forceinline__ unsigned cvt_pk_bf16(float lo, float hi) { unsigned r; asm volatile("v_cvt_pk_bf16_f32 %0, %1, %2" : "=v"(r) : "v"(lo), "v"(hi)); return r; }
; __device__ __forceinline__ void st16_wt(void* p, u32x4 v) { asm volatile("global_store_dwordx4 %0, %1, off sc1\n\ts_nop 1" :: "v"(p), "v"(v) : "memory"); }
; __device__ __forceinline__ void tr_item(const float* __restrict__ W, int K, int N, bf16_t* WT, const float* __restrict__ kscale, int rowmode, int item, int lane) {
;     ...
;     else drow = ((n0 >> 7) << 8) + (n0 & 127) + (rowmode == 2 ? 128 : 0);
; #pragma unroll
;     for (int e = 0; e < 4; ++e) { u32x4 o; o.x = cvt_pk_bf16(v[0][e], v[1][e]); o.y = cvt_pk_bf16(v[2][e], v[3][e]); o.z = cvt_pk_bf16(v[4][e], v[5][e]); o.w = cvt_pk_bf16(v[6][e], v[7][e]);
;         pg8::st16_wt(WT + (size_t)(drow + e) * K + k0, o); }
.Lsl_p0_rmd23:
	s_mul_i32 s19, s19, s59
	s_lshl_b32 s20, s17, 7
	s_add_i32 s19, s19, s20
	v_add_u32_e32 v111, s19, v111
	s_add_i32 s4, s4, 2048
	s_cmp_eq_u32 s55, 0
	s_cbranch_scc1 .Lsl_p0_w825
	s_waitcnt vmcnt(20)
	s_branch .Lsl_p0_wd26

; __device__ __forceinline__ unsigned cvt_pk_bf16(float lo, float hi) { unsigned r; asm volatile("v_cvt_pk_bf16_f32 %0, %1, %2" : "=v"(r) : "v"(lo), "v"(hi)); return r; }
; __device__ __forceinline__ void st16_wt(void* p, u32x4 v) { asm volatile("global_store_dwordx4 %0, %1, off sc1\n\ts_nop 1" :: "v"(p), "v"(v) : "memory"); }
; __device__ __forceinline__ void tr_item(const float* __restrict__ W, int K, int N, bf16_t* WT, const float* __restrict__ kscale, int rowmode, int item, int lane) {
;     ...
; #pragma unroll
;     for (int e = 0; e < 4; ++e) { u32x4 o; o.x = cvt_pk_bf16(v[0][e], v[1][e]); o.y = cvt_pk_bf16(v[2][e], v[3][e]); o.z = cvt_pk_bf16(v[4][e], v[5][e]); o.w = cvt_pk_bf16(v[6][e], v[7][e]);
;         pg8::st16_wt(WT + (size_t)(drow + e) * K + k0, o); }
.Lsl_p0_nmul27:
	v_cvt_pk_bf16_f32 v86, v2, v6
	v_cvt_pk_bf16_f32 v87, v10, v14
	v_cvt_pk_bf16_f32 v88, v18, v22
	v_cvt_pk_bf16_f32 v89, v26, v30
	v_cvt_pk_bf16_f32 v90, v3, v7
	v_cvt_pk_bf16_f32 v91, v11, v15
	v_cvt_pk_bf16_f32 v92, v19, v23
	v_cvt_pk_bf16_f32 v93, v27, v31
	v_cvt_pk_bf16_f32 v94, v4, v8
	v_cvt_pk_bf16_f32 v95, v12, v16
	v_cvt_pk_bf16_f32 v96, v20, v24
	v_cvt_pk_bf16_f32 v97, v28, v32
	v_cvt_pk_bf16_f32 v98, v5, v9
	v_cvt_pk_bf16_f32 v99, v13, v17
	v_cvt_pk_bf16_f32 v100, v21, v25
	v_cvt_pk_bf16_f32 v101, v29, v33
	global_store_dwordx4 v44, v[86:89], s[24:25] sc1
	v_add_u32_e32 v44, s57, v44
	global_store_dwordx4 v44, v[90:93], s[24:25] sc1
	v_add_u32_e32 v44, s57, v44
	global_store_dwordx4 v44, v[94:97], s[24:25] sc1
	v_add_u32_e32 v44, s57, v44
	global_store_dwordx4 v44, v[98:101], s[24:25] sc1
	s_cmp_eq_u32 s55, 0
	s_cbranch_scc1 .Lsl_p0_w828
	s_waitcnt vmcnt(14)
	s_branch .Lsl_p0_wd29

; __device__ __forceinline__ unsigned cvt_pk_bf16(float lo, float hi) { unsigned r; asm volatile("v_cvt_pk_bf16_f32 %0, %1, %2" : "=v"(r) : "v"(lo), "v"(hi)); return r; }
; __device__ __forceinline__ void st16_wt(void* p, u32x4 v) { asm volatile("global_store_dwordx4 %0, %1, off sc1\n\ts_nop 1" :: "v"(p), "v"(v) : "memory"); }
; __device__ __forceinline__ void tr_item(const float* __restrict__ W, int K, int N, bf16_t* WT, const float* __restrict__ kscale, int rowmode, int item, int lane) {
;     ...
; #pragma unroll
;     for (int e = 0; e < 4; ++e) { u32x4 o; o.x = cvt_pk_bf16(v[0][e], v[1][e]); o.y = cvt_pk_bf16(v[2][e], v[3][e]); o.z = cvt_pk_bf16(v[4][e], v[5][e]); o.w = cvt_pk_bf16(v[6][e], v[7][e]);
;         pg8::st16_wt(WT + (size_t)(drow + e) * K + k0, o); }
.Lsl_p0_nmul30:
	v_cvt_pk_bf16_f32 v86, v46, v50
	v_cvt_pk_bf16_f32 v87, v54, v58
	v_cvt_pk_bf16_f32 v88, v62, v66
	v_cvt_pk_bf16_f32 v89, v70, v74
	v_cvt_pk_bf16_f32 v90, v47, v51
	v_cvt_pk_bf16_f32 v91, v55, v59
	v_cvt_pk_bf16_f32 v92, v63, v67
	v_cvt_pk_bf16_f32 v93, v71, v75
	v_cvt_pk_bf16_f32 v94, v48, v52
	v_cvt_pk_bf16_f32 v95, v56, v60
	v_cvt_pk_bf16_f32 v96, v64, v68
	v_cvt_pk_bf16_f32 v97, v72, v76
	v_cvt_pk_bf16_f32 v98, v49, v53
	v_cvt_pk_bf16_f32 v99, v57, v61
	v_cvt_pk_bf16_f32 v100, v65, v69
	v_cvt_pk_bf16_f32 v101, v73, v77
	global_store_dwordx4 v45, v[86:89], s[24:25] sc1
	v_add_u32_e32 v45, s58, v45
	global_store_dwordx4 v45, v[90:93], s[24:25] sc1
	v_add_u32_e32 v45, s58, v45
	global_store_dwordx4 v45, v[94:97], s[24:25] sc1
	v_add_u32_e32 v45, s58, v45
	global_store_dwordx4 v45, v[98:101], s[24:25] sc1
	s_waitcnt vmcnt(8)
	s_cmp_eq_u32 s55, 0
	s_cbranch_scc1 .Lsl_p0_nmul31
	v_mul_f32_e32 v112, v112, v144
	v_mul_f32_e32 v113, v113, v144
	v_mul_f32_e32 v114, v114, v144
	v_mul_f32_e32 v115, v115, v144
	v_mul_f32_e32 v116, v116, v145
	v_mul_f32_e32 v117, v117, v145
	v_mul_f32_e32 v118, v118, v145
	v_mul_f32_e32 v119, v119, v145
	v_mul_f32_e32 v120, v120, v146
	v_mul_f32_e32 v121, v121, v146
	v_mul_f32_e32 v122, v122, v146
	v_mul_f32_e32 v123, v123, v146
	v_mul_f32_e32 v124, v124, v147
	v_mul_f32_e32 v125, v125, v147
	v_mul_f32_e32 v126, v126, v147
	v_mul_f32_e32 v127, v127, v147
	v_mul_f32_e32 v128, v128, v148
	v_mul_f32_e32 v129, v129, v148
	v_mul_f32_e32 v130, v130, v148
	v_mul_f32_e32 v131, v131, v148
	v_mul_f32_e32 v132, v132, v149
	v_mul_f32_e32 v133, v133, v149
	v_mul_f32_e32 v134, v134, v149
	v_mul_f32_e32 v135, v135, v149
	v_mul_f32_e32 v136, v136, v150
	v_mul_f32_e32 v137, v137, v150
	v_mul_f32_e32 v138, v138, v150
	v_mul_f32_e32 v139, v139, v150
	v_mul_f32_e32 v140, v140, v151
	v_mul_f32_e32 v141, v141, v151
	v_mul_f32_e32 v142, v142, v151
	v_mul_f32_e32 v143, v143, v151
.Lsl_p0_nmul31:
	v_cvt_pk_bf16_f32 v86, v112, v116
	v_cvt_pk_bf16_f32 v87, v120, v124
	v_cvt_pk_bf16_f32 v88, v128, v132
	v_cvt_pk_bf16_f32 v89, v136, v140
	v_cvt_pk_bf16_f32 v90, v113, v117
	v_cvt_pk_bf16_f32 v91, v121, v125
	v_cvt_pk_bf16_f32 v92, v129, v133
	v_cvt_pk_bf16_f32 v93, v137, v141
	v_cvt_pk_bf16_f32 v94, v114, v118
	v_cvt_pk_bf16_f32 v95, v122, v126
	v_cvt_pk_bf16_f32 v96, v130, v134
	v_cvt_pk_bf16_f32 v97, v138, v142
	v_cvt_pk_bf16_f32 v98, v115, v119
	v_cvt_pk_bf16_f32 v99, v123, v127
	v_cvt_pk_bf16_f32 v100, v131, v135
	v_cvt_pk_bf16_f32 v101, v139, v143
	global_store_dwordx4 v111, v[86:89], s[24:25] sc1
	v_add_u32_e32 v111, s59, v111
	global_store_dwordx4 v111, v[90:93], s[24:25] sc1
	v_add_u32_e32 v111, s59, v111
	global_store_dwordx4 v111, v[94:97], s[24:25] sc1
	v_add_u32_e32 v111, s59, v111
	global_store_dwordx4 v111, v[98:101], s[24:25] sc1
	s_branch .Lsl_p0_loop

; __device__ __forceinline__ unsigned cvt_pk_bf16(float lo, float hi) { unsigned r; asm volatile("v_cvt_pk_bf16_f32 %0, %1, %2" : "=v"(r) : "v"(lo), "v"(hi)); return r; }
; __device__ __forceinline__ void st16_wt(void* p, u32x4 v) { asm volatile("global_store_dwordx4 %0, %1, off sc1\n\ts_nop 1" :: "v"(p), "v"(v) : "memory"); }
; __device__ __forceinline__ void tr_item(const float* __restrict__ W, int K, int N, bf16_t* WT, const float* __restrict__ kscale, int rowmode, int item, int lane) {
;     ...
; #pragma unroll
;     for (int e = 0; e < 4; ++e) { u32x4 o; o.x = cvt_pk_bf16(v[0][e], v[1][e]); o.y = cvt_pk_bf16(v[2][e], v[3][e]); o.z = cvt_pk_bf16(v[4][e], v[5][e]); o.w = cvt_pk_bf16(v[6][e], v[7][e]);
;         pg8::st16_wt(WT + (size_t)(drow + e) * K + k0, o); }
.Lsl_p0_nmul34:
	v_cvt_pk_bf16_f32 v86, v2, v6
	v_cvt_pk_bf16_f32 v87, v10, v14
	v_cvt_pk_bf16_f32 v88, v18, v22
	v_cvt_pk_bf16_f32 v89, v26, v30
	v_cvt_pk_bf16_f32 v90, v3, v7
	v_cvt_pk_bf16_f32 v91, v11, v15
	v_cvt_pk_bf16_f32 v92, v19, v23
	v_cvt_pk_bf16_f32 v93, v27, v31
	v_cvt_pk_bf16_f32 v94, v4, v8
	v_cvt_pk_bf16_f32 v95, v12, v16
	v_cvt_pk_bf16_f32 v96, v20, v24
	v_cvt_pk_bf16_f32 v97, v28, v32
	v_cvt_pk_bf16_f32 v98, v5, v9
	v_cvt_pk_bf16_f32 v99, v13, v17
	v_cvt_pk_bf16_f32 v100, v21, v25
	v_cvt_pk_bf16_f32 v101, v29, v33
	global_store_dwordx4 v44, v[86:89], s[24:25] sc1
	v_add_u32_e32 v44, s57, v44
	global_store_dwordx4 v44, v[90:93], s[24:25] sc1
	v_add_u32_e32 v44, s57, v44
	global_store_dwordx4 v44, v[94:97], s[24:25] sc1
	v_add_u32_e32 v44, s57, v44
	global_store_dwordx4 v44, v[98:101], s[24:25] sc1
	s_waitcnt vmcnt(4)
	s_cmp_eq_u32 s55, 0
	s_cbranch_scc1 .Lsl_p0_nmul35
	v_mul_f32_e32 v46, v46, v78
	v_mul_f32_e32 v47, v47, v78
	v_mul_f32_e32 v48, v48, v78
	v_mul_f32_e32 v49, v49, v78
	v_mul_f32_e32 v50, v50, v79
	v_mul_f32_e32 v51, v51, v79
	v_mul_f32_e32 v52, v52, v79
	v_mul_f32_e32 v53, v53, v79
	v_mul_f32_e32 v54, v54, v80
	v_mul_f32_e32 v55, v55, v80
	v_mul_f32_e32 v56, v56, v80
	v_mul_f32_e32 v57, v57, v80
	v_mul_f32_e32 v58, v58, v81
	v_mul_f32_e32 v59, v59, v81
	v_mul_f32_e32 v60, v60, v81
	v_mul_f32_e32 v61, v61, v81
	v_mul_f32_e32 v62, v62, v82
	v_mul_f32_e32 v63, v63, v82
	v_mul_f32_e32 v64, v64, v82
	v_mul_f32_e32 v65, v65, v82
	v_mul_f32_e32 v66, v66, v83
	v_mul_f32_e32 v67, v67, v83
	v_mul_f32_e32 v68, v68, v83
	v_mul_f32_e32 v69, v69, v83
	v_mul_f32_e32 v70, v70, v84
	v_mul_f32_e32 v71, v71, v84
	v_mul_f32_e32 v72, v72, v84
	v_mul_f32_e32 v73, v73, v84
	v_mul_f32_e32 v74, v74, v85
	v_mul_f32_e32 v75, v75, v85
	v_mul_f32_e32 v76, v76, v85
	v_mul_f32_e32 v77, v77, v85
.Lsl_p0_nmul35:
	v_cvt_pk_bf16_f32 v86, v46, v50
	v_cvt_pk_bf16_f32 v87, v54, v58
	v_cvt_pk_bf16_f32 v88, v62, v66
	v_cvt_pk_bf16_f32 v89, v70, v74
	v_cvt_pk_bf16_f32 v90, v47, v51
	v_cvt_pk_bf16_f32 v91, v55, v59
	v_cvt_pk_bf16_f32 v92, v63, v67
	v_cvt_pk_bf16_f32 v93, v71, v75
	v_cvt_pk_bf16_f32 v94, v48, v52
	v_cvt_pk_bf16_f32 v95, v56, v60
	v_cvt_pk_bf16_f32 v96, v64, v68
	v_cvt_pk_bf16_f32 v97, v72, v76
	v_cvt_pk_bf16_f32 v98, v49, v53
	v_cvt_pk_bf16_f32 v99, v57, v61
	v_cvt_pk_bf16_f32 v100, v65, v69
	v_cvt_pk_bf16_f32 v101, v73, v77
	global_store_dwordx4 v45, v[86:89], s[24:25] sc1
	v_add_u32_e32 v45, s58, v45
	global_store_dwordx4 v45, v[90:93], s[24:25] sc1
	v_add_u32_e32 v45, s58, v45
	global_store_dwordx4 v45, v[94:97], s[24:25] sc1
	v_add_u32_e32 v45, s58, v45
	global_store_dwordx4 v45, v[98:101], s[24:25] sc1
	s_branch .Lsl_p0_next

; __device__ __forceinline__ unsigned cvt_pk_bf16(float lo, float hi) { unsigned r; asm volatile("v_cvt_pk_bf16_f32 %0, %1, %2" : "=v"(r) : "v"(lo), "v"(hi)); return r; }
; __device__ __forceinline__ void st16_wt(void* p, u32x4 v) { asm volatile("global_store_dwordx4 %0, %1, off sc1\n\ts_nop 1" :: "v"(p), "v"(v) : "memory"); }
; __device__ __forceinline__ void tr_item(const float* __restrict__ W, int K, int N, bf16_t* WT, const float* __restrict__ kscale, int rowmode, int item, int lane) {
;     ...
; #pragma unroll
;     for (int e = 0; e < 4; ++e) { u32x4 o; o.x = cvt_pk_bf16(v[0][e], v[1][e]); o.y = cvt_pk_bf16(v[2][e], v[3][e]); o.z = cvt_pk_bf16(v[4][e], v[5][e]); o.w = cvt_pk_bf16(v[6][e], v[7][e]);
;         pg8::st16_wt(WT + (size_t)(drow + e) * K + k0, o); }
.Lsl_p0_nmul36:
	v_cvt_pk_bf16_f32 v86, v2, v6
	v_cvt_pk_bf16_f32 v87, v10, v14
	v_cvt_pk_bf16_f32 v88, v18, v22
	v_cvt_pk_bf16_f32 v89, v26, v30
	v_cvt_pk_bf16_f32 v90, v3, v7
	v_cvt_pk_bf16_f32 v91, v11, v15
	v_cvt_pk_bf16_f32 v92, v19, v23
	v_cvt_pk_bf16_f32 v93, v27, v31
	v_cvt_pk_bf16_f32 v94, v4, v8
	v_cvt_pk_bf16_f32 v95, v12, v16
	v_cvt_pk_bf16_f32 v96, v20, v24
	v_cvt_pk_bf16_f32 v97, v28, v32
	v_cvt_pk_bf16_f32 v98, v5, v9
	v_cvt_pk_bf16_f32 v99, v13, v17
	v_cvt_pk_bf16_f32 v100, v21, v25
	v_cvt_pk_bf16_f32 v101, v29, v33
	global_store_dwordx4 v44, v[86:89], s[24:25] sc1
	v_add_u32_e32 v44, s57, v44
	global_store_dwordx4 v44, v[90:93], s[24:25] sc1
	v_add_u32_e32 v44, s57, v44
	global_store_dwordx4 v44, v[94:97], s[24:25] sc1
	v_add_u32_e32 v44, s57, v44
	global_store_dwordx4 v44, v[98:101], s[24:25] sc1

;     ...
;     for (int mi = 0; mi < 7 * DEPTH; ++mi) {
;         if (!((mask >> mi) & 1u)) continue;
;         const int l = mi / 7, kind = mi - 7 * l;
;         const float* W; const float* ks = nullptr; bf16_t* WT; int K, N, rm = 0;
;         if (kind == 0)      { W = a.in[2] + (size_t)l * 2048 * 7680;  K = 2048; N = 7680; WT = (bf16_t*)(ws + WS_WIN + l * SZ_WIN); ks = a.in[1] + l * 2048; rm = 3; }
;         else if (kind == 1) { W = a.in[10] + (size_t)l * 1024 * 2048; K = 1024; N = 2048; WT = (bf16_t*)(ws + WS_WA + l * SZ_WA); }
;         else if (kind == 2) { W = a.in[11] + (size_t)l * 1024 * 2048; K = 1024; N = 2048; WT = (bf16_t*)(ws + WS_WB + l * SZ_WB); }
;         else if (kind == 3) { W = a.in[12] + (size_t)l * 2048 * 2048; K = 2048; N = 2048; WT = (bf16_t*)(ws + WS_WO + l * SZ_WO); }
;         else if (kind == 4) { W = a.in[14] + (size_t)l * 2048 * 5632; K = 2048; N = 5632; WT = (bf16_t*)(ws + WS_WGU + l * SZ_WGU); ks = a.in[13] + l * 2048; rm = 1; }
;         else if (kind == 5) { W = a.in[15] + (size_t)l * 2048 * 5632; K = 2048; N = 5632; WT = (bf16_t*)(ws + WS_WGU + l * SZ_WGU); ks = a.in[13] + l * 2048; rm = 2; }
;         else                { W = a.in[16] + (size_t)l * 5632 * 2048; K = 5632; N = 2048; WT = (bf16_t*)(ws + WS_WD + l * SZ_WD); }
;         const int nitems = (K >> 6) * (N >> 5);
;         int ilo = 0, ihi = nitems; if ((fmask >> mi) & 1u) { ilo = (nitems * flo) >> 4; ihi = (nitems * fhi) >> 4; }
;         const int cnt = ihi - ilo;
;         int first = (gw - base) % NGW; if (first < 0) first += NGW;
;         for (int it = first; it < cnt; it += NGW) tr_item(W, K, N, WT, ks, rm, ilo + it, lane);
;         base = (base + cnt) % NGW;
; __global__ void __launch_bounds__(NTHREADS, 2) mk_fwd(Args args) {
;     ...
;                 if (blk >= thr) p0_prologue(args, (blk - thr) * NWAVES + wave, (G - thr) * NWAVES, lane, l == 0 ? 0x0030u : 0x1800u, false, l == 0 ? 0x0010u : 0x0800u, 10, 16); }
.Lsl_in_set0:
	v_readlane_b32 s22, v250, 30
	v_readlane_b32 s23, v250, 31
	v_readlane_b32 s24, v250, 36
	v_readlane_b32 s25, v250, 37
	v_readlane_b32 s26, v250, 28
	v_readlane_b32 s27, v250, 29
	v_mul_u32_u24_e32 v104, 0x2c000, v102
	v_lshl_add_u32 v104, v103, 4, v104
	v_mul_u32_u24_e32 v105, 0x4000, v103
	v_lshl_add_u32 v105, v102, 4, v105
	s_mov_b32 s48, 0
	s_add_u32 s24, s24, 0x5dc0000
	s_addc_u32 s25, s25, 0
	s_mov_b32 s36, 0x5800
	s_mov_b32 s37, 0x160000
	s_movk_i32 s38, 2979
	s_mov_b32 s39, 19
	s_movk_i32 s40, 176
	s_movk_i32 s41, 0x1000
	s_mov_b32 s42, 1
	s_mov_b32 s43, 1
	s_movk_i32 s44, 3520
	s_movk_i32 s29, 2112
	s_sub_i32 s4, s2, 0
	s_and_b32 s4, s4, 511
	s_branch .Lsl_in_loop
.Lsl_in_set1:
	v_readlane_b32 s22, v250, 32
	v_readlane_b32 s23, v250, 33
	v_readlane_b32 s24, v250, 36
	v_readlane_b32 s25, v250, 37
	v_readlane_b32 s26, v250, 28
	v_readlane_b32 s27, v250, 29
	v_mul_u32_u24_e32 v104, 0x2c000, v102
	v_lshl_add_u32 v104, v103, 4, v104
	v_mul_u32_u24_e32 v105, 0x4000, v103
	v_lshl_add_u32 v105, v102, 4, v105
	s_mov_b32 s48, 0
	s_add_u32 s24, s24, 0x5dc0000
	s_addc_u32 s25, s25, 0
	s_mov_b32 s36, 0x5800
	s_mov_b32 s37, 0x160000
	s_movk_i32 s38, 2979
	s_mov_b32 s39, 19
	s_movk_i32 s40, 176
	s_movk_i32 s41, 0x1000
	s_mov_b32 s42, 2
	s_mov_b32 s43, 1
	s_movk_i32 s44, 0
	s_movk_i32 s29, 5632
	s_sub_i32 s4, s2, 64
	s_and_b32 s4, s4, 511
	s_branch .Lsl_in_loop
.Lsl_in_set16:
	v_readlane_b32 s22, v250, 30
	v_readlane_b32 s23, v250, 31
	v_readlane_b32 s24, v250, 36
	v_readlane_b32 s25, v250, 37
	v_readlane_b32 s26, v250, 28
	v_readlane_b32 s27, v250, 29
	v_mul_u32_u24_e32 v104, 0x2c000, v102
	v_lshl_add_u32 v104, v103, 4, v104
	v_mul_u32_u24_e32 v105, 0x4000, v103
	v_lshl_add_u32 v105, v102, 4, v105
	s_mov_b32 s48, 0
	s_add_u32 s22, s22, 0x2c00000
	s_addc_u32 s23, s23, 0
	s_add_u32 s24, s24, 0x89c0000
	s_addc_u32 s25, s25, 0
	s_add_u32 s26, s26, 0x2000
	s_addc_u32 s27, s27, 0
	s_mov_b32 s36, 0x5800
	s_mov_b32 s37, 0x160000
	s_movk_i32 s38, 2979
	s_mov_b32 s39, 19
	s_movk_i32 s40, 176
	s_movk_i32 s41, 0x1000
	s_mov_b32 s42, 1
	s_mov_b32 s43, 1
	s_movk_i32 s44, 3520
	s_movk_i32 s29, 2112
	s_sub_i32 s4, s2, 0
	s_and_b32 s4, s4, 511
	s_branch .Lsl_in_loop
.Lsl_in_set17:
	v_readlane_b32 s22, v250, 32
	v_readlane_b32 s23, v250, 33
	v_readlane_b32 s24, v250, 36
	v_readlane_b32 s25, v250, 37
	v_readlane_b32 s26, v250, 28
	v_readlane_b32 s27, v250, 29
	v_mul_u32_u24_e32 v104, 0x2c000, v102
	v_lshl_add_u32 v104, v103, 4, v104
	v_mul_u32_u24_e32 v105, 0x4000, v103
	v_lshl_add_u32 v105, v102, 4, v105
	s_mov_b32 s48, 0
	s_add_u32 s22, s22, 0x2c00000
	s_addc_u32 s23, s23, 0
	s_add_u32 s24, s24, 0x89c0000
	s_addc_u32 s25, s25, 0
	s_add_u32 s26, s26, 0x2000
	s_addc_u32 s27, s27, 0
	s_mov_b32 s36, 0x5800
	s_mov_b32 s37, 0x160000
	s_movk_i32 s38, 2979
	s_mov_b32 s39, 19
	s_movk_i32 s40, 176
	s_movk_i32 s41, 0x1000
	s_mov_b32 s42, 2
	s_mov_b32 s43, 1
	s_movk_i32 s44, 0
	s_movk_i32 s29, 5632
	s_sub_i32 s4, s2, 64
	s_and_b32 s4, s4, 511
	s_branch .Lsl_in_loop
.Lsl_in_loop:
	s_cmp_ge_u32 s4, s29
	s_cbranch_scc1 .Lsl_in_next
	s_add_i32 s16, s4, s44
	s_mov_b32 s45, s41
	v_mov_b32_e32 v44, v105
	s_mul_i32 s17, s16, s38
	s_lshr_b32 s17, s17, s39
	s_mul_i32 s19, s17, s40
	s_sub_i32 s18, s16, s19
	s_mul_i32 s19, s17, s37
	s_lshl_b32 s20, s18, 7
	s_add_i32 s19, s19, s20
	v_add_u32_e32 v42, s19, v104
	s_cmp_eq_u32 s43, 0
	s_cbranch_scc1 .Lsl_in_nks3
	s_lshl_b32 s19, s17, 8
	v_add_u32_e32 v43, s19, v110
	global_load_dwordx4 v[34:37], v43, s[26:27]
	global_load_dwordx4 v[38:41], v43, s[26:27] offset:16

; __device__ __forceinline__ void tr_item(const float* __restrict__ W, int K, int N, bf16_t* WT, const float* __restrict__ kscale, int rowmode, int item, int lane) {
;     const int nblk = N >> 5, kb = item / nblk, nb = item - kb * nblk;
;     const int c = lane >> 3, q = lane & 7, k0 = kb * 64 + c * 8, n0 = nb * 32 + q * 4;
;     f32x4 v[8];
; #pragma unroll
;     for (int i = 0; i < 8; ++i) v[i] = __builtin_nontemporal_load((const f32x4*)(W + (size_t)(k0 + i) * N + n0));
;     if (kscale) { const f32x4 s0 = *(const f32x4*)(kscale + k0), s1 = *(const f32x4*)(kscale + k0 + 4);
; #pragma unroll
;         for (int i = 0; i < 4; ++i) { v[i] = v[i] * s0[i]; v[4 + i] = v[4 + i] * s1[i]; } }
;     int drow;
;     if (rowmode == 0) drow = n0;
;     else if (rowmode == 3) { const int g = n0 - pg8::C_GA; drow = g < 0 ? n0 : pg8::C_GA + (((g & 2047) >> 7) << 8) + ((g >> 11) << 7) + (g & 127); }
;     else drow = ((n0 >> 7) << 8) + (n0 & 127) + (rowmode == 2 ? 128 : 0);
.Lsl_in_rmd4:
	s_mul_i32 s19, s19, s45
	s_lshl_b32 s20, s17, 7
	s_add_i32 s19, s19, s20
	v_add_u32_e32 v44, s19, v44
	s_add_i32 s4, s4, 512
	s_cmp_ge_u32 s4, s29
	s_cbranch_scc1 .Lsl_in_single
	s_add_i32 s16, s4, s44
	s_mov_b32 s46, s41
	v_mov_b32_e32 v45, v105
	s_mul_i32 s17, s16, s38
	s_lshr_b32 s17, s17, s39
	s_mul_i32 s19, s17, s40
	s_sub_i32 s18, s16, s19
	s_mul_i32 s19, s17, s37
	s_lshl_b32 s20, s18, 7
	s_add_i32 s19, s19, s20
	v_add_u32_e32 v42, s19, v104
	s_cmp_eq_u32 s43, 0
	s_cbranch_scc1 .Lsl_in_nks8
	s_lshl_b32 s19, s17, 8
	v_add_u32_e32 v43, s19, v110
	global_load_dwordx4 v[78:81], v43, s[26:27]
	global_load_dwordx4 v[82:85], v43, s[26:27] offset:16

; __device__ __forceinline__ void tr_item(const float* __restrict__ W, int K, int N, bf16_t* WT, const float* __restrict__ kscale, int rowmode, int item, int lane) {
;     const int nblk = N >> 5, kb = item / nblk, nb = item - kb * nblk;
;     const int c = lane >> 3, q = lane & 7, k0 = kb * 64 + c * 8, n0 = nb * 32 + q * 4;
;     f32x4 v[8];
; #pragma unroll
;     for (int i = 0; i < 8; ++i) v[i] = __builtin_nontemporal_load((const f32x4*)(W + (size_t)(k0 + i) * N + n0));
;     if (kscale) { const f32x4 s0 = *(const f32x4*)(kscale + k0), s1 = *(const f32x4*)(kscale + k0 + 4);
; #pragma unroll
;         for (int i = 0; i < 4; ++i) { v[i] = v[i] * s0[i]; v[4 + i] = v[4 + i] * s1[i]; } }
;     int drow;
;     if (rowmode == 0) drow = n0;
;     else if (rowmode == 3) { const int g = n0 - pg8::C_GA; drow = g < 0 ? n0 : pg8::C_GA + (((g & 2047) >> 7) << 8) + ((g >> 11) << 7) + (g & 127); }
;     else drow = ((n0 >> 7) << 8) + (n0 & 127) + (rowmode == 2 ? 128 : 0);
.Lsl_in_rmd9:
	s_mul_i32 s19, s19, s46
	s_lshl_b32 s20, s17, 7
	s_add_i32 s19, s19, s20
	v_add_u32_e32 v45, s19, v45
	s_add_i32 s4, s4, 512
	s_cmp_ge_u32 s4, s29
	s_cbranch_scc1 .Lsl_in_pair
	s_add_i32 s16, s4, s44
	s_mov_b32 s47, s41
	v_mov_b32_e32 v111, v105
	s_mul_i32 s17, s16, s38
	s_lshr_b32 s17, s17, s39
	s_mul_i32 s19, s17, s40
	s_sub_i32 s18, s16, s19
	s_mul_i32 s19, s17, s37
	s_lshl_b32 s20, s18, 7
	s_add_i32 s19, s19, s20
	v_add_u32_e32 v42, s19, v104
	s_cmp_eq_u32 s43, 0
	s_cbranch_scc1 .Lsl_in_nks13
	s_lshl_b32 s19, s17, 8
	v_add_u32_e32 v43, s19, v110
	global_load_dwordx4 v[144:147], v43, s[26:27]
	global_load_dwordx4 v[148:151], v43, s[26:27] offset:16

; __device__ __forceinline__ unsigned cvt_pk_bf16(float lo, float hi) { unsigned r; asm volatile("v_cvt_pk_bf16_f32 %0, %1, %2" : "=v"(r) : "v"(lo), "v"(hi)); return r; }
; __device__ __forceinline__ void st16_wt(void* p, u32x4 v) { asm volatile("global_store_dwordx4 %0, %1, off sc1\n\ts_nop 1" :: "v"(p), "v"(v) : "memory"); }
; __device__ __forceinline__ void tr_item(const float* __restrict__ W, int K, int N, bf16_t* WT, const float* __restrict__ kscale, int rowmode, int item, int lane) {
;     ...
;     else drow = ((n0 >> 7) << 8) + (n0 & 127) + (rowmode == 2 ? 128 : 0);
; #pragma unroll
;     for (int e = 0; e < 4; ++e) { u32x4 o; o.x = cvt_pk_bf16(v[0][e], v[1][e]); o.y = cvt_pk_bf16(v[2][e], v[3][e]); o.z = cvt_pk_bf16(v[4][e], v[5][e]); o.w = cvt_pk_bf16(v[6][e], v[7][e]);
;         pg8::st16_wt(WT + (size_t)(drow + e) * K + k0, o); }
.Lsl_in_rmd14:
	s_mul_i32 s19, s19, s47
	s_lshl_b32 s20, s17, 7
	s_add_i32 s19, s19, s20
	v_add_u32_e32 v111, s19, v111
	s_add_i32 s4, s4, 512
	s_cmp_eq_u32 s43, 0
	s_cbranch_scc1 .Lsl_in_w816
	s_waitcnt vmcnt(20)
	s_branch .Lsl_in_wd17

; __device__ __forceinline__ unsigned cvt_pk_bf16(float lo, float hi) { unsigned r; asm volatile("v_cvt_pk_bf16_f32 %0, %1, %2" : "=v"(r) : "v"(lo), "v"(hi)); return r; }
; __device__ __forceinline__ void st16_wt(void* p, u32x4 v) { asm volatile("global_store_dwordx4 %0, %1, off sc1\n\ts_nop 1" :: "v"(p), "v"(v) : "memory"); }
; __device__ __forceinline__ void tr_item(const float* __restrict__ W, int K, int N, bf16_t* WT, const float* __restrict__ kscale, int rowmode, int item, int lane) {
;     ...
; #pragma unroll
;     for (int e = 0; e < 4; ++e) { u32x4 o; o.x = cvt_pk_bf16(v[0][e], v[1][e]); o.y = cvt_pk_bf16(v[2][e], v[3][e]); o.z = cvt_pk_bf16(v[4][e], v[5][e]); o.w = cvt_pk_bf16(v[6][e], v[7][e]);
;         pg8::st16_wt(WT + (size_t)(drow + e) * K + k0, o); }
.Lsl_in_nmul18:
	v_cvt_pk_bf16_f32 v86, v2, v6
	v_cvt_pk_bf16_f32 v87, v10, v14
	v_cvt_pk_bf16_f32 v88, v18, v22
	v_cvt_pk_bf16_f32 v89, v26, v30
	v_cvt_pk_bf16_f32 v90, v3, v7
	v_cvt_pk_bf16_f32 v91, v11, v15
	v_cvt_pk_bf16_f32 v92, v19, v23
	v_cvt_pk_bf16_f32 v93, v27, v31
	v_cvt_pk_bf16_f32 v94, v4, v8
	v_cvt_pk_bf16_f32 v95, v12, v16
	v_cvt_pk_bf16_f32 v96, v20, v24
	v_cvt_pk_bf16_f32 v97, v28, v32
	v_cvt_pk_bf16_f32 v98, v5, v9
	v_cvt_pk_bf16_f32 v99, v13, v17
	v_cvt_pk_bf16_f32 v100, v21, v25
	v_cvt_pk_bf16_f32 v101, v29, v33
	global_store_dwordx4 v44, v[86:89], s[24:25] sc1
	v_add_u32_e32 v44, s45, v44
	global_store_dwordx4 v44, v[90:93], s[24:25] sc1
	v_add_u32_e32 v44, s45, v44
	global_store_dwordx4 v44, v[94:97], s[24:25] sc1
	v_add_u32_e32 v44, s45, v44
	global_store_dwordx4 v44, v[98:101], s[24:25] sc1
	s_cmp_eq_u32 s43, 0
	s_cbranch_scc1 .Lsl_in_w819
	s_waitcnt vmcnt(14)
	s_branch .Lsl_in_wd20

; __device__ __forceinline__ unsigned cvt_pk_bf16(float lo, float hi) { unsigned r; asm volatile("v_cvt_pk_bf16_f32 %0, %1, %2" : "=v"(r) : "v"(lo), "v"(hi)); return r; }
; __device__ __forceinline__ void st16_wt(void* p, u32x4 v) { asm volatile("global_store_dwordx4 %0, %1, off sc1\n\ts_nop 1" :: "v"(p), "v"(v) : "memory"); }
; __device__ __forceinline__ void tr_item(const float* __restrict__ W, int K, int N, bf16_t* WT, const float* __restrict__ kscale, int rowmode, int item, int lane) {
;     ...
; #pragma unroll
;     for (int e = 0; e < 4; ++e) { u32x4 o; o.x = cvt_pk_bf16(v[0][e], v[1][e]); o.y = cvt_pk_bf16(v[2][e], v[3][e]); o.z = cvt_pk_bf16(v[4][e], v[5][e]); o.w = cvt_pk_bf16(v[6][e], v[7][e]);
;         pg8::st16_wt(WT + (size_t)(drow + e) * K + k0, o); }
.Lsl_in_nmul21:
	v_cvt_pk_bf16_f32 v86, v46, v50
	v_cvt_pk_bf16_f32 v87, v54, v58
	v_cvt_pk_bf16_f32 v88, v62, v66
	v_cvt_pk_bf16_f32 v89, v70, v74
	v_cvt_pk_bf16_f32 v90, v47, v51
	v_cvt_pk_bf16_f32 v91, v55, v59
	v_cvt_pk_bf16_f32 v92, v63, v67
	v_cvt_pk_bf16_f32 v93, v71, v75
	v_cvt_pk_bf16_f32 v94, v48, v52
	v_cvt_pk_bf16_f32 v95, v56, v60
	v_cvt_pk_bf16_f32 v96, v64, v68
	v_cvt_pk_bf16_f32 v97, v72, v76
	v_cvt_pk_bf16_f32 v98, v49, v53
	v_cvt_pk_bf16_f32 v99, v57, v61
	v_cvt_pk_bf16_f32 v100, v65, v69
	v_cvt_pk_bf16_f32 v101, v73, v77
	global_store_dwordx4 v45, v[86:89], s[24:25] sc1
	v_add_u32_e32 v45, s46, v45
	global_store_dwordx4 v45, v[90:93], s[24:25] sc1
	v_add_u32_e32 v45, s46, v45
	global_store_dwordx4 v45, v[94:97], s[24:25] sc1
	v_add_u32_e32 v45, s46, v45
	global_store_dwordx4 v45, v[98:101], s[24:25] sc1
	s_waitcnt vmcnt(8)
	s_cmp_eq_u32 s43, 0
	s_cbranch_scc1 .Lsl_in_nmul22
	v_mul_f32_e32 v112, v112, v144
	v_mul_f32_e32 v113, v113, v144
	v_mul_f32_e32 v114, v114, v144
	v_mul_f32_e32 v115, v115, v144
	v_mul_f32_e32 v116, v116, v145
	v_mul_f32_e32 v117, v117, v145
	v_mul_f32_e32 v118, v118, v145
	v_mul_f32_e32 v119, v119, v145
	v_mul_f32_e32 v120, v120, v146
	v_mul_f32_e32 v121, v121, v146
	v_mul_f32_e32 v122, v122, v146
	v_mul_f32_e32 v123, v123, v146
	v_mul_f32_e32 v124, v124, v147
	v_mul_f32_e32 v125, v125, v147
	v_mul_f32_e32 v126, v126, v147
	v_mul_f32_e32 v127, v127, v147
	v_mul_f32_e32 v128, v128, v148
	v_mul_f32_e32 v129, v129, v148
	v_mul_f32_e32 v130, v130, v148
	v_mul_f32_e32 v131, v131, v148
	v_mul_f32_e32 v132, v132, v149
	v_mul_f32_e32 v133, v133, v149
	v_mul_f32_e32 v134, v134, v149
	v_mul_f32_e32 v135, v135, v149
	v_mul_f32_e32 v136, v136, v150
	v_mul_f32_e32 v137, v137, v150
	v_mul_f32_e32 v138, v138, v150
	v_mul_f32_e32 v139, v139, v150
	v_mul_f32_e32 v140, v140, v151
	v_mul_f32_e32 v141, v141, v151
	v_mul_f32_e32 v142, v142, v151
	v_mul_f32_e32 v143, v143, v151
.Lsl_in_nmul22:
	v_cvt_pk_bf16_f32 v86, v112, v116
	v_cvt_pk_bf16_f32 v87, v120, v124
	v_cvt_pk_bf16_f32 v88, v128, v132
	v_cvt_pk_bf16_f32 v89, v136, v140
	v_cvt_pk_bf16_f32 v90, v113, v117
	v_cvt_pk_bf16_f32 v91, v121, v125
	v_cvt_pk_bf16_f32 v92, v129, v133
	v_cvt_pk_bf16_f32 v93, v137, v141
	v_cvt_pk_bf16_f32 v94, v114, v118
	v_cvt_pk_bf16_f32 v95, v122, v126
	v_cvt_pk_bf16_f32 v96, v130, v134
	v_cvt_pk_bf16_f32 v97, v138, v142
	v_cvt_pk_bf16_f32 v98, v115, v119
	v_cvt_pk_bf16_f32 v99, v123, v127
	v_cvt_pk_bf16_f32 v100, v131, v135
	v_cvt_pk_bf16_f32 v101, v139, v143
	global_store_dwordx4 v111, v[86:89], s[24:25] sc1
	v_add_u32_e32 v111, s47, v111
	global_store_dwordx4 v111, v[90:93], s[24:25] sc1
	v_add_u32_e32 v111, s47, v111
	global_store_dwordx4 v111, v[94:97], s[24:25] sc1
	v_add_u32_e32 v111, s47, v111
	global_store_dwordx4 v111, v[98:101], s[24:25] sc1
	s_branch .Lsl_in_loop

; __device__ __forceinline__ unsigned cvt_pk_bf16(float lo, float hi) { unsigned r; asm volatile("v_cvt_pk_bf16_f32 %0, %1, %2" : "=v"(r) : "v"(lo), "v"(hi)); return r; }
; __device__ __forceinline__ void st16_wt(void* p, u32x4 v) { asm volatile("global_store_dwordx4 %0, %1, off sc1\n\ts_nop 1" :: "v"(p), "v"(v) : "memory"); }
; __device__ __forceinline__ void tr_item(const float* __restrict__ W, int K, int N, bf16_t* WT, const float* __restrict__ kscale, int rowmode, int item, int lane) {
;     ...
; #pragma unroll
;     for (int e = 0; e < 4; ++e) { u32x4 o; o.x = cvt_pk_bf16(v[0][e], v[1][e]); o.y = cvt_pk_bf16(v[2][e], v[3][e]); o.z = cvt_pk_bf16(v[4][e], v[5][e]); o.w = cvt_pk_bf16(v[6][e], v[7][e]);
;         pg8::st16_wt(WT + (size_t)(drow + e) * K + k0, o); }
.Lsl_in_nmul25:
	v_cvt_pk_bf16_f32 v86, v2, v6
	v_cvt_pk_bf16_f32 v87, v10, v14
	v_cvt_pk_bf16_f32 v88, v18, v22
	v_cvt_pk_bf16_f32 v89, v26, v30
	v_cvt_pk_bf16_f32 v90, v3, v7
	v_cvt_pk_bf16_f32 v91, v11, v15
	v_cvt_pk_bf16_f32 v92, v19, v23
	v_cvt_pk_bf16_f32 v93, v27, v31
	v_cvt_pk_bf16_f32 v94, v4, v8
	v_cvt_pk_bf16_f32 v95, v12, v16
	v_cvt_pk_bf16_f32 v96, v20, v24
	v_cvt_pk_bf16_f32 v97, v28, v32
	v_cvt_pk_bf16_f32 v98, v5, v9
	v_cvt_pk_bf16_f32 v99, v13, v17
	v_cvt_pk_bf16_f32 v100, v21, v25
	v_cvt_pk_bf16_f32 v101, v29, v33
	global_store_dwordx4 v44, v[86:89], s[24:25] sc1
	v_add_u32_e32 v44, s45, v44
	global_store_dwordx4 v44, v[90:93], s[24:25] sc1
	v_add_u32_e32 v44, s45, v44
	global_store_dwordx4 v44, v[94:97], s[24:25] sc1
	v_add_u32_e32 v44, s45, v44
	global_store_dwordx4 v44, v[98:101], s[24:25] sc1
	s_waitcnt vmcnt(4)
	s_cmp_eq_u32 s43, 0
	s_cbranch_scc1 .Lsl_in_nmul26
	v_mul_f32_e32 v46, v46, v78
	v_mul_f32_e32 v47, v47, v78
	v_mul_f32_e32 v48, v48, v78
	v_mul_f32_e32 v49, v49, v78
	v_mul_f32_e32 v50, v50, v79
	v_mul_f32_e32 v51, v51, v79
	v_mul_f32_e32 v52, v52, v79
	v_mul_f32_e32 v53, v53, v79
	v_mul_f32_e32 v54, v54, v80
	v_mul_f32_e32 v55, v55, v80
	v_mul_f32_e32 v56, v56, v80
	v_mul_f32_e32 v57, v57, v80
	v_mul_f32_e32 v58, v58, v81
	v_mul_f32_e32 v59, v59, v81
	v_mul_f32_e32 v60, v60, v81
	v_mul_f32_e32 v61, v61, v81
	v_mul_f32_e32 v62, v62, v82
	v_mul_f32_e32 v63, v63, v82
	v_mul_f32_e32 v64, v64, v82
	v_mul_f32_e32 v65, v65, v82
	v_mul_f32_e32 v66, v66, v83
	v_mul_f32_e32 v67, v67, v83
	v_mul_f32_e32 v68, v68, v83
	v_mul_f32_e32 v69, v69, v83
	v_mul_f32_e32 v70, v70, v84
	v_mul_f32_e32 v71, v71, v84
	v_mul_f32_e32 v72, v72, v84
	v_mul_f32_e32 v73, v73, v84
	v_mul_f32_e32 v74, v74, v85
	v_mul_f32_e32 v75, v75, v85
	v_mul_f32_e32 v76, v76, v85
	v_mul_f32_e32 v77, v77, v85
.Lsl_in_nmul26:
	v_cvt_pk_bf16_f32 v86, v46, v50
	v_cvt_pk_bf16_f32 v87, v54, v58
	v_cvt_pk_bf16_f32 v88, v62, v66
	v_cvt_pk_bf16_f32 v89, v70, v74
	v_cvt_pk_bf16_f32 v90, v47, v51
	v_cvt_pk_bf16_f32 v91, v55, v59
	v_cvt_pk_bf16_f32 v92, v63, v67
	v_cvt_pk_bf16_f32 v93, v71, v75
	v_cvt_pk_bf16_f32 v94, v48, v52
	v_cvt_pk_bf16_f32 v95, v56, v60
	v_cvt_pk_bf16_f32 v96, v64, v68
	v_cvt_pk_bf16_f32 v97, v72, v76
	v_cvt_pk_bf16_f32 v98, v49, v53
	v_cvt_pk_bf16_f32 v99, v57, v61
	v_cvt_pk_bf16_f32 v100, v65, v69
	v_cvt_pk_bf16_f32 v101, v73, v77
	global_store_dwordx4 v45, v[86:89], s[24:25] sc1
	v_add_u32_e32 v45, s46, v45
	global_store_dwordx4 v45, v[90:93], s[24:25] sc1
	v_add_u32_e32 v45, s46, v45
	global_store_dwordx4 v45, v[94:97], s[24:25] sc1
	v_add_u32_e32 v45, s46, v45
	global_store_dwordx4 v45, v[98:101], s[24:25] sc1
	s_branch .Lsl_in_next

; __device__ __forceinline__ unsigned cvt_pk_bf16(float lo, float hi) { unsigned r; asm volatile("v_cvt_pk_bf16_f32 %0, %1, %2" : "=v"(r) : "v"(lo), "v"(hi)); return r; }
; __device__ __forceinline__ void st16_wt(void* p, u32x4 v) { asm volatile("global_store_dwordx4 %0, %1, off sc1\n\ts_nop 1" :: "v"(p), "v"(v) : "memory"); }
; __device__ __forceinline__ void tr_item(const float* __restrict__ W, int K, int N, bf16_t* WT, const float* __restrict__ kscale, int rowmode, int item, int lane) {
;     ...
; #pragma unroll
;     for (int e = 0; e < 4; ++e) { u32x4 o; o.x = cvt_pk_bf16(v[0][e], v[1][e]); o.y = cvt_pk_bf16(v[2][e], v[3][e]); o.z = cvt_pk_bf16(v[4][e], v[5][e]); o.w = cvt_pk_bf16(v[6][e], v[7][e]);
;         pg8::st16_wt(WT + (size_t)(drow + e) * K + k0, o); }
.Lsl_in_nmul27:
	v_cvt_pk_bf16_f32 v86, v2, v6
	v_cvt_pk_bf16_f32 v87, v10, v14
	v_cvt_pk_bf16_f32 v88, v18, v22
	v_cvt_pk_bf16_f32 v89, v26, v30
	v_cvt_pk_bf16_f32 v90, v3, v7
	v_cvt_pk_bf16_f32 v91, v11, v15
	v_cvt_pk_bf16_f32 v92, v19, v23
	v_cvt_pk_bf16_f32 v93, v27, v31
	v_cvt_pk_bf16_f32 v94, v4, v8
	v_cvt_pk_bf16_f32 v95, v12, v16
	v_cvt_pk_bf16_f32 v96, v20, v24
	v_cvt_pk_bf16_f32 v97, v28, v32
	v_cvt_pk_bf16_f32 v98, v5, v9
	v_cvt_pk_bf16_f32 v99, v13, v17
	v_cvt_pk_bf16_f32 v100, v21, v25
	v_cvt_pk_bf16_f32 v101, v29, v33
	global_store_dwordx4 v44, v[86:89], s[24:25] sc1
	v_add_u32_e32 v44, s45, v44
	global_store_dwordx4 v44, v[90:93], s[24:25] sc1
	v_add_u32_e32 v44, s45, v44
	global_store_dwordx4 v44, v[94:97], s[24:25] sc1
	v_add_u32_e32 v44, s45, v44
	global_store_dwordx4 v44, v[98:101], s[24:25] sc1

;     ...
;     for (int mi = 0; mi < 7 * DEPTH; ++mi) {
;         if (!((mask >> mi) & 1u)) continue;
;         const int l = mi / 7, kind = mi - 7 * l;
;         const float* W; const float* ks = nullptr; bf16_t* WT; int K, N, rm = 0;
;         if (kind == 0)      { W = a.in[2] + (size_t)l * 2048 * 7680;  K = 2048; N = 7680; WT = (bf16_t*)(ws + WS_WIN + l * SZ_WIN); ks = a.in[1] + l * 2048; rm = 3; }
;         else if (kind == 1) { W = a.in[10] + (size_t)l * 1024 * 2048; K = 1024; N = 2048; WT = (bf16_t*)(ws + WS_WA + l * SZ_WA); }
;         else if (kind == 2) { W = a.in[11] + (size_t)l * 1024 * 2048; K = 1024; N = 2048; WT = (bf16_t*)(ws + WS_WB + l * SZ_WB); }
;         else if (kind == 3) { W = a.in[12] + (size_t)l * 2048 * 2048; K = 2048; N = 2048; WT = (bf16_t*)(ws + WS_WO + l * SZ_WO); }
;         else if (kind == 4) { W = a.in[14] + (size_t)l * 2048 * 5632; K = 2048; N = 5632; WT = (bf16_t*)(ws + WS_WGU + l * SZ_WGU); ks = a.in[13] + l * 2048; rm = 1; }
;         else if (kind == 5) { W = a.in[15] + (size_t)l * 2048 * 5632; K = 2048; N = 5632; WT = (bf16_t*)(ws + WS_WGU + l * SZ_WGU); ks = a.in[13] + l * 2048; rm = 2; }
;         else                { W = a.in[16] + (size_t)l * 5632 * 2048; K = 5632; N = 2048; WT = (bf16_t*)(ws + WS_WD + l * SZ_WD); }
;         const int nitems = (K >> 6) * (N >> 5);
;         int ilo = 0, ihi = nitems; if ((fmask >> mi) & 1u) { ilo = (nitems * flo) >> 4; ihi = (nitems * fhi) >> 4; }
;         const int cnt = ihi - ilo;
;         int first = (gw - base) % NGW; if (first < 0) first += NGW;
;         for (int it = first; it < cnt; it += NGW) tr_item(W, K, N, WT, ks, rm, ilo + it, lane);
;         base = (base + cnt) % NGW;
; __global__ void __launch_bounds__(NTHREADS, 2) mk_fwd(Args args) {
;     ...
;                 if (blk >= thr) p0_prologue(args, (blk - thr) * NWAVES + wave, (G - thr) * NWAVES, lane, l == 0 ? 0x07C0u : 0x2000u, false); }
.Lsl_gu_dispatch:
	s_cmp_eq_u32 s28, 0
	s_cbranch_scc1 .Lsl_gu_set0
	s_cmp_eq_u32 s28, 1
	s_cbranch_scc1 .Lsl_gu_set1
	s_cmp_eq_u32 s28, 2
	s_cbranch_scc1 .Lsl_gu_set2
	s_cmp_eq_u32 s28, 16
	s_cbranch_scc1 .Lsl_gu_set16
	s_branch .LBB0_716
.Lsl_gu_set0:
	s_mov_b64 s[22:23], s[88:89]
	v_readlane_b32 s24, v250, 36
	v_readlane_b32 s25, v250, 37
	v_mul_u32_u24_e32 v104, 0x10000, v102
	v_lshl_add_u32 v104, v103, 4, v104
	v_mul_u32_u24_e32 v105, 0xb000, v103
	v_lshl_add_u32 v105, v102, 4, v105
	s_mov_b32 s48, 0
	s_add_u32 s24, s24, 0xb5c0000
	s_addc_u32 s25, s25, 0
	s_mov_b32 s36, 0x2000
	s_mov_b32 s37, 0x80000
	s_movk_i32 s38, 1
	s_mov_b32 s39, 6
	s_movk_i32 s40, 64
	s_movk_i32 s41, 0x2c00
	s_mov_b32 s42, 0
	s_mov_b32 s43, 0
	s_movk_i32 s44, 0
	s_movk_i32 s29, 5632
	s_sub_i32 s4, s2, 0
	s_and_b32 s4, s4, 1023
	s_branch .Lsl_gu_loop
.Lsl_gu_set1:
	v_readlane_b32 s22, v250, 6
	v_readlane_b32 s23, v250, 7
	v_readlane_b32 s24, v250, 36
	v_readlane_b32 s25, v250, 37
	v_readlane_b32 s26, v250, 4
	v_readlane_b32 s27, v250, 5
	v_mul_u32_u24_e32 v104, 0x3c000, v102
	v_lshl_add_u32 v104, v103, 4, v104
	v_mul_u32_u24_e32 v105, 0x4000, v103
	v_lshl_add_u32 v105, v102, 4, v105
	s_mov_b32 s48, 0
	s_add_u32 s22, s22, 0x3c00000
	s_addc_u32 s23, s23, 0
	s_add_u32 s24, s24, 0x1fc0000
	s_addc_u32 s25, s25, 0
	s_add_u32 s26, s26, 0x2000
	s_addc_u32 s27, s27, 0
	s_mov_b32 s36, 0x7800
	s_mov_b32 s37, 0x1e0000
	s_movk_i32 s38, 8739
	s_mov_b32 s39, 21
	s_movk_i32 s40, 240
	s_movk_i32 s41, 0x1000
	s_mov_b32 s42, 3
	s_mov_b32 s43, 1
	s_movk_i32 s44, 0
	s_movk_i32 s29, 7680
	s_sub_i32 s4, s2, 512
	s_and_b32 s4, s4, 1023
	s_branch .Lsl_gu_loop
.Lsl_gu_set2:
	v_readlane_b32 s22, v250, 22
	v_readlane_b32 s23, v250, 23
	v_readlane_b32 s24, v250, 36
	v_readlane_b32 s25, v250, 37
	v_mul_u32_u24_e32 v104, 0x10000, v102
	v_lshl_add_u32 v104, v103, 4, v104
	v_mul_u32_u24_e32 v105, 0x2000, v103
	v_lshl_add_u32 v105, v102, 4, v105
	v_mul_u32_u24_e32 v106, 0x4000, v103
	v_lshl_add_u32 v106, v102, 4, v106
	s_mov_b32 s48, 1
	s_add_u32 s24, s24, 0xfffc0000
	s_addc_u32 s25, s25, -1
	s_mov_b32 s36, 0x2000
	s_mov_b32 s37, 0x80000
	s_movk_i32 s38, 1
	s_mov_b32 s39, 6
	s_movk_i32 s40, 64
	s_movk_i32 s41, 0x800
	s_mov_b32 s42, 0
	s_mov_b32 s43, 0
	s_movk_i32 s44, 0
	s_movk_i32 s29, 4096
	s_sub_i32 s4, s2, 0
	s_and_b32 s4, s4, 1023
	s_branch .Lsl_gu_loop
.Lsl_gu_set16:
	s_mov_b64 s[22:23], s[88:89]
	v_readlane_b32 s24, v250, 36
	v_readlane_b32 s25, v250, 37
	v_mul_u32_u24_e32 v104, 0x10000, v102
	v_lshl_add_u32 v104, v103, 4, v104
	v_mul_u32_u24_e32 v105, 0xb000, v103
	v_lshl_add_u32 v105, v102, 4, v105
	s_mov_b32 s48, 0
	s_add_u32 s22, s22, 0x2c00000
	s_addc_u32 s23, s23, 0
	s_add_u32 s24, s24, 0xcbc0000
	s_addc_u32 s25, s25, 0
	s_mov_b32 s36, 0x2000
	s_mov_b32 s37, 0x80000
	s_movk_i32 s38, 1
	s_mov_b32 s39, 6
	s_movk_i32 s40, 64
	s_movk_i32 s41, 0x2c00
	s_mov_b32 s42, 0
	s_mov_b32 s43, 0
	s_movk_i32 s44, 0
	s_movk_i32 s29, 5632
	s_sub_i32 s4, s2, 0
	s_and_b32 s4, s4, 1023
	s_branch .Lsl_gu_loop
.Lsl_gu_loop:
	s_cmp_ge_u32 s4, s29
	s_cbranch_scc1 .Lsl_gu_next
	s_add_i32 s16, s4, s44
	s_mov_b32 s45, s41
	v_mov_b32_e32 v44, v105
	s_cmp_eq_u32 s48, 0
	s_cbranch_scc1 .Lsl_gu_nmu1
	s_cmp_ge_u32 s16, 2048
	s_cbranch_scc1 .Lsl_gu_pc5
	s_cmp_ge_u32 s16, 1024
	s_cbranch_scc1 .Lsl_gu_pc4
	v_readlane_b32 s22, v250, 22
	v_readlane_b32 s23, v250, 23
	s_movk_i32 s45, 0x800
	s_mov_b32 s21, 0x4200000
	v_add_u32_e32 v44, s21, v105
	s_nop 0
	s_add_u32 s22, s22, 0x800000
	s_addc_u32 s23, s23, 0
	s_branch .Lsl_gu_pj2
.Lsl_gu_pc4:
	v_readlane_b32 s22, v250, 24
	v_readlane_b32 s23, v250, 25
	s_sub_i32 s16, s16, 1024
	s_movk_i32 s45, 0x800
	s_mov_b32 s21, 0x4a00000
	v_add_u32_e32 v44, s21, v105
	s_nop 0
	s_add_u32 s22, s22, 0x800000
	s_addc_u32 s23, s23, 0
	s_branch .Lsl_gu_pj2
.Lsl_gu_pc5:
	v_readlane_b32 s22, v250, 26
	v_readlane_b32 s23, v250, 27
	s_sub_i32 s16, s16, 2048
	s_movk_i32 s45, 0x1000
	s_mov_b32 s21, 0x5600000
	v_add_u32_e32 v44, s21, v106
	s_nop 0
	s_add_u32 s22, s22, 0x1000000
	s_addc_u32 s23, s23, 0
.Lsl_gu_pj2:
.Lsl_gu_nmu1:
	s_mul_i32 s17, s16, s38
	s_lshr_b32 s17, s17, s39
	s_mul_i32 s19, s17, s40
	s_sub_i32 s18, s16, s19
	s_mul_i32 s19, s17, s37
	s_lshl_b32 s20, s18, 7
	s_add_i32 s19, s19, s20
	v_add_u32_e32 v42, s19, v104
	s_cmp_eq_u32 s43, 0
	s_cbranch_scc1 .Lsl_gu_nks6
	s_lshl_b32 s19, s17, 8
	v_add_u32_e32 v43, s19, v110
	global_load_dwordx4 v[34:37], v43, s[26:27]
	global_load_dwordx4 v[38:41], v43, s[26:27] offset:16

; __device__ __forceinline__ void tr_item(const float* __restrict__ W, int K, int N, bf16_t* WT, const float* __restrict__ kscale, int rowmode, int item, int lane) {
;     const int nblk = N >> 5, kb = item / nblk, nb = item - kb * nblk;
;     const int c = lane >> 3, q = lane & 7, k0 = kb * 64 + c * 8, n0 = nb * 32 + q * 4;
;     f32x4 v[8];
; #pragma unroll
;     for (int i = 0; i < 8; ++i) v[i] = __builtin_nontemporal_load((const f32x4*)(W + (size_t)(k0 + i) * N + n0));
;     if (kscale) { const f32x4 s0 = *(const f32x4*)(kscale + k0), s1 = *(const f32x4*)(kscale + k0 + 4);
; #pragma unroll
;         for (int i = 0; i < 4; ++i) { v[i] = v[i] * s0[i]; v[4 + i] = v[4 + i] * s1[i]; } }
;     int drow;
;     if (rowmode == 0) drow = n0;
;     else if (rowmode == 3) { const int g = n0 - pg8::C_GA; drow = g < 0 ? n0 : pg8::C_GA + (((g & 2047) >> 7) << 8) + ((g >> 11) << 7) + (g & 127); }
;     else drow = ((n0 >> 7) << 8) + (n0 & 127) + (rowmode == 2 ? 128 : 0);
.Lsl_gu_rmd7:
	s_mul_i32 s19, s19, s45
	s_lshl_b32 s20, s17, 7
	s_add_i32 s19, s19, s20
	v_add_u32_e32 v44, s19, v44
	s_add_i32 s4, s4, 1024
	s_cmp_ge_u32 s4, s29
	s_cbranch_scc1 .Lsl_gu_single
	s_add_i32 s16, s4, s44
	s_mov_b32 s46, s41
	v_mov_b32_e32 v45, v105
	s_cmp_eq_u32 s48, 0
	s_cbranch_scc1 .Lsl_gu_nmu9
	s_cmp_ge_u32 s16, 2048
	s_cbranch_scc1 .Lsl_gu_pc13
	s_cmp_ge_u32 s16, 1024
	s_cbranch_scc1 .Lsl_gu_pc12
	v_readlane_b32 s22, v250, 22
	v_readlane_b32 s23, v250, 23
	s_movk_i32 s46, 0x800
	s_mov_b32 s21, 0x4200000
	v_add_u32_e32 v45, s21, v105
	s_nop 0
	s_add_u32 s22, s22, 0x800000
	s_addc_u32 s23, s23, 0
	s_branch .Lsl_gu_pj10
.Lsl_gu_pc12:
	v_readlane_b32 s22, v250, 24
	v_readlane_b32 s23, v250, 25
	s_sub_i32 s16, s16, 1024
	s_movk_i32 s46, 0x800
	s_mov_b32 s21, 0x4a00000
	v_add_u32_e32 v45, s21, v105
	s_nop 0
	s_add_u32 s22, s22, 0x800000
	s_addc_u32 s23, s23, 0
	s_branch .Lsl_gu_pj10
.Lsl_gu_pc13:
	v_readlane_b32 s22, v250, 26
	v_readlane_b32 s23, v250, 27
	s_sub_i32 s16, s16, 2048
	s_movk_i32 s46, 0x1000
	s_mov_b32 s21, 0x5600000
	v_add_u32_e32 v45, s21, v106
	s_nop 0
	s_add_u32 s22, s22, 0x1000000
	s_addc_u32 s23, s23, 0
.Lsl_gu_pj10:
.Lsl_gu_nmu9:
	s_mul_i32 s17, s16, s38
	s_lshr_b32 s17, s17, s39
	s_mul_i32 s19, s17, s40
	s_sub_i32 s18, s16, s19
	s_mul_i32 s19, s17, s37
	s_lshl_b32 s20, s18, 7
	s_add_i32 s19, s19, s20
	v_add_u32_e32 v42, s19, v104
	s_cmp_eq_u32 s43, 0
	s_cbranch_scc1 .Lsl_gu_nks14
	s_lshl_b32 s19, s17, 8
	v_add_u32_e32 v43, s19, v110
	global_load_dwordx4 v[78:81], v43, s[26:27]
	global_load_dwordx4 v[82:85], v43, s[26:27] offset:16

; __device__ __forceinline__ void tr_item(const float* __restrict__ W, int K, int N, bf16_t* WT, const float* __restrict__ kscale, int rowmode, int item, int lane) {
;     const int nblk = N >> 5, kb = item / nblk, nb = item - kb * nblk;
;     const int c = lane >> 3, q = lane & 7, k0 = kb * 64 + c * 8, n0 = nb * 32 + q * 4;
;     f32x4 v[8];
; #pragma unroll
;     for (int i = 0; i < 8; ++i) v[i] = __builtin_nontemporal_load((const f32x4*)(W + (size_t)(k0 + i) * N + n0));
;     if (kscale) { const f32x4 s0 = *(const f32x4*)(kscale + k0), s1 = *(const f32x4*)(kscale + k0 + 4);
; #pragma unroll
;         for (int i = 0; i < 4; ++i) { v[i] = v[i] * s0[i]; v[4 + i] = v[4 + i] * s1[i]; } }
;     int drow;
;     if (rowmode == 0) drow = n0;
;     else if (rowmode == 3) { const int g = n0 - pg8::C_GA; drow = g < 0 ? n0 : pg8::C_GA + (((g & 2047) >> 7) << 8) + ((g >> 11) << 7) + (g & 127); }
;     else drow = ((n0 >> 7) << 8) + (n0 & 127) + (rowmode == 2 ? 128 : 0);
.Lsl_gu_rmd15:
	s_mul_i32 s19, s19, s46
	s_lshl_b32 s20, s17, 7
	s_add_i32 s19, s19, s20
	v_add_u32_e32 v45, s19, v45
	s_add_i32 s4, s4, 1024
	s_cmp_ge_u32 s4, s29
	s_cbranch_scc1 .Lsl_gu_pair
	s_add_i32 s16, s4, s44
	s_mov_b32 s47, s41
	v_mov_b32_e32 v111, v105
	s_cmp_eq_u32 s48, 0
	s_cbranch_scc1 .Lsl_gu_nmu17
	s_cmp_ge_u32 s16, 2048
	s_cbranch_scc1 .Lsl_gu_pc21
	s_cmp_ge_u32 s16, 1024
	s_cbranch_scc1 .Lsl_gu_pc20
	v_readlane_b32 s22, v250, 22
	v_readlane_b32 s23, v250, 23
	s_movk_i32 s47, 0x800
	s_mov_b32 s21, 0x4200000
	v_add_u32_e32 v111, s21, v105
	s_nop 0
	s_add_u32 s22, s22, 0x800000
	s_addc_u32 s23, s23, 0
	s_branch .Lsl_gu_pj18
.Lsl_gu_pc20:
	v_readlane_b32 s22, v250, 24
	v_readlane_b32 s23, v250, 25
	s_sub_i32 s16, s16, 1024
	s_movk_i32 s47, 0x800
	s_mov_b32 s21, 0x4a00000
	v_add_u32_e32 v111, s21, v105
	s_nop 0
	s_add_u32 s22, s22, 0x800000
	s_addc_u32 s23, s23, 0
	s_branch .Lsl_gu_pj18
.Lsl_gu_pc21:
	v_readlane_b32 s22, v250, 26
	v_readlane_b32 s23, v250, 27
	s_sub_i32 s16, s16, 2048
	s_movk_i32 s47, 0x1000
	s_mov_b32 s21, 0x5600000
	v_add_u32_e32 v111, s21, v106
	s_nop 0
	s_add_u32 s22, s22, 0x1000000
	s_addc_u32 s23, s23, 0
.Lsl_gu_pj18:
.Lsl_gu_nmu17:
	s_mul_i32 s17, s16, s38
	s_lshr_b32 s17, s17, s39
	s_mul_i32 s19, s17, s40
	s_sub_i32 s18, s16, s19
	s_mul_i32 s19, s17, s37
	s_lshl_b32 s20, s18, 7
	s_add_i32 s19, s19, s20
	v_add_u32_e32 v42, s19, v104
	s_cmp_eq_u32 s43, 0
	s_cbranch_scc1 .Lsl_gu_nks22
	s_lshl_b32 s19, s17, 8
	v_add_u32_e32 v43, s19, v110
	global_load_dwordx4 v[144:147], v43, s[26:27]
	global_load_dwordx4 v[148:151], v43, s[26:27] offset:16

; __device__ __forceinline__ unsigned cvt_pk_bf16(float lo, float hi) { unsigned r; asm volatile("v_cvt_pk_bf16_f32 %0, %1, %2" : "=v"(r) : "v"(lo), "v"(hi)); return r; }
; __device__ __forceinline__ void st16_wt(void* p, u32x4 v) { asm volatile("global_store_dwordx4 %0, %1, off sc1\n\ts_nop 1" :: "v"(p), "v"(v) : "memory"); }
; __device__ __forceinline__ void tr_item(const float* __restrict__ W, int K, int N, bf16_t* WT, const float* __restrict__ kscale, int rowmode, int item, int lane) {
;     ...
;     else drow = ((n0 >> 7) << 8) + (n0 & 127) + (rowmode == 2 ? 128 : 0);
; #pragma unroll
;     for (int e = 0; e < 4; ++e) { u32x4 o; o.x = cvt_pk_bf16(v[0][e], v[1][e]); o.y = cvt_pk_bf16(v[2][e], v[3][e]); o.z = cvt_pk_bf16(v[4][e], v[5][e]); o.w = cvt_pk_bf16(v[6][e], v[7][e]);
;         pg8::st16_wt(WT + (size_t)(drow + e) * K + k0, o); }
.Lsl_gu_rmd23:
	s_mul_i32 s19, s19, s47
	s_lshl_b32 s20, s17, 7
	s_add_i32 s19, s19, s20
	v_add_u32_e32 v111, s19, v111
	s_add_i32 s4, s4, 1024
	s_cmp_eq_u32 s43, 0
	s_cbranch_scc1 .Lsl_gu_w825
	s_waitcnt vmcnt(20)
	s_branch .Lsl_gu_wd26
